# P3 final epilogue: 16 gate loads in one batch with counted waits (was 8 serialized round trips)
# speedup vs baseline: 1.0124x; 1.0002x over previous
; __device__ __forceinline__ unsigned pk4_fp8g(float a, float b, float c, float d) { int r = __builtin_amdgcn_cvt_pk_fp8_f32(a, b, 0, false); r = __builtin_amdgcn_cvt_pk_fp8_f32(c, d, r, true); return (unsigned)r; }
; #define G2B(bw, sh) (fmaxf((float)(((bw) >> (sh)) & 0xffu), 0.5f) * (1.f / 2040.f))
;     __device__ __forceinline__ void operator()(const f32x4 (&acc)[2][2][4][2], const Unit& u, int wr, int wc, int fr, int fq) const {
;         asm volatile("" : "+v"(fr), "+v"(fq));
;         const int row0 = u.pm * BM + wr * 64 + fr, col0 = u.pn * BM + wc * 32 + 8 * fq;
; #pragma unroll
;         for (int ai = 0; ai < 2; ++ai)
; #pragma unroll
;             for (int m = 0; m < 4; ++m) { const size_t r = (size_t)(row0 + ai * HALF + m * 16);
; #pragma unroll
;                 for (int bj = 0; bj < 2; ++bj) {
;                     const u32x2g b = *(const u32x2g*)(Gt + r * GC + DM + col0 + bj * HALF);
;                     f32x4 v0 = acc[ai][bj][m][0], v1 = acc[ai][bj][m][1];
;     ...
;                     v0[0] *= G2B(b.x, 0); v0[1] *= G2B(b.x, 8); v0[2] *= G2B(b.x, 16); v0[3] *= G2B(b.x, 24);
;                     v1[0] *= G2B(b.y, 0); v1[1] *= G2B(b.y, 8); v1[2] *= G2B(b.y, 16); v1[3] *= G2B(b.y, 24);
;     ...
;                     u32x2g w; w.x = pk4_fp8g(v0[0], v0[1], v0[2], v0[3]); w.y = pk4_fp8g(v1[0], v1[1], v1[2], v1[3]);
;                     *(u32x2g*)((unsigned char*)O + r * DM + col0 + bj * HALF) = w; }
;                 asm volatile("" ::: "memory"); }
.LBB0_310:
	v_mov_b32_e32 v128, v151
	v_mov_b32_e32 v130, v150
	v_mov_b32_e32 v138, v129
	v_add_u32_e32 v136, s88, v130
	v_ashrrev_i32_e32 v137, 31, v136
	v_lshl_add_u32 v134, v128, 3, s9
	v_lshlrev_b64 v[130:131], 11, v[136:137]
	v_ashrrev_i32_e32 v135, 31, v134
	v_lshl_add_u64 v[130:131], s[42:43], 0, v[130:131]
	v_lshl_add_u64 v[130:131], v[130:131], 0, v[134:135]
	global_load_dwordx2 v[178:179], v[130:131], off offset:1024
	global_load_dwordx2 v[180:181], v[130:131], off offset:1152
	v_lshl_add_u64 v[212:213], v[130:131], 0, s[46:47]
	global_load_dwordx2 v[182:183], v[212:213], off offset:1024
	global_load_dwordx2 v[184:185], v[212:213], off offset:1152
	v_lshl_add_u64 v[210:211], v[130:131], 0, s[48:49]
	global_load_dwordx2 v[186:187], v[210:211], off offset:1024
	global_load_dwordx2 v[188:189], v[210:211], off offset:1152
	v_lshl_add_u64 v[212:213], v[130:131], 0, s[14:15]
	global_load_dwordx2 v[190:191], v[212:213], off offset:1024
	global_load_dwordx2 v[192:193], v[212:213], off offset:1152
	v_lshl_add_u64 v[210:211], v[130:131], 0, s[50:51]
	global_load_dwordx2 v[194:195], v[210:211], off offset:1024
	global_load_dwordx2 v[196:197], v[210:211], off offset:1152
	v_lshl_add_u64 v[212:213], v[130:131], 0, s[54:55]
	global_load_dwordx2 v[198:199], v[212:213], off offset:1024
	global_load_dwordx2 v[200:201], v[212:213], off offset:1152
	v_lshl_add_u64 v[210:211], v[130:131], 0, s[56:57]
	global_load_dwordx2 v[202:203], v[210:211], off offset:1024
	global_load_dwordx2 v[204:205], v[210:211], off offset:1152
	v_lshl_add_u64 v[212:213], v[130:131], 0, s[58:59]
	global_load_dwordx2 v[206:207], v[212:213], off offset:1024
	global_load_dwordx2 v[208:209], v[212:213], off offset:1152
	s_waitcnt vmcnt(14)
	v_mov_b64_e32 v[132:133], v[178:179]
	s_nop 0
	v_mov_b64_e32 v[130:131], v[180:181]
	v_lshlrev_b64 v[144:145], 10, v[136:137]
	v_mov_b32_e32 v139, v129
	v_mov_b32_e32 v140, v129
	v_mov_b32_e32 v141, v129
	v_add_u32_e32 v142, 16, v136
	v_ashrrev_i32_e32 v143, 31, v142
	v_lshl_add_u64 v[144:145], s[28:29], 0, v[144:145]
	v_lshlrev_b64 v[156:157], 11, v[142:143]
	v_lshl_add_u64 v[144:145], v[144:145], 0, v[134:135]
	s_and_b64 vcc, exec, s[2:3]
	s_mov_b64 s[2:3], -1
	v_cvt_f32_ubyte0_e32 v128, v132
	v_cvt_f32_ubyte1_e32 v137, v132
	v_cvt_f32_ubyte0_e32 v158, v133
	v_cvt_f32_ubyte1_e32 v159, v133
	v_cvt_f32_ubyte0_e32 v161, v130
	v_cvt_f32_ubyte1_e32 v162, v130
	v_cvt_f32_ubyte0_e32 v164, v131
	v_cvt_f32_ubyte1_e32 v165, v131
	v_max_f32_e32 v128, 0.5, v128
	v_max_f32_e32 v137, 0.5, v137
	v_max_f32_e32 v158, 0.5, v158
	v_max_f32_e32 v159, 0.5, v159
	v_max_f32_e32 v161, 0.5, v161
	v_max_f32_e32 v162, 0.5, v162
	v_max_f32_e32 v164, 0.5, v164
	v_max_f32_e32 v165, 0.5, v165
	v_mul_f32_e32 v128, 0x3a008081, v128
	v_mul_f32_e32 v137, 0x3a008081, v137
	v_mul_f32_e32 v158, 0x3a008081, v158
	v_mul_f32_e32 v159, 0x3a008081, v159
	v_mul_f32_e32 v161, 0x3a008081, v161
	v_mul_f32_e32 v162, 0x3a008081, v162
	v_mul_f32_e32 v164, 0x3a008081, v164
	v_mul_f32_e32 v165, 0x3a008081, v165
	v_mul_f32_e32 v112, v112, v128
	v_mul_f32_e32 v113, v113, v137
	v_mul_f32_e32 v116, v116, v158
	v_mul_f32_e32 v117, v117, v159
	v_cvt_f32_ubyte2_e32 v155, v132
	v_cvt_f32_ubyte3_e32 v132, v132
	v_cvt_f32_ubyte2_e32 v160, v133
	v_cvt_f32_ubyte3_e32 v133, v133
	v_mul_f32_e32 v120, v120, v161
	v_mul_f32_e32 v121, v121, v162
	v_mul_f32_e32 v124, v124, v164
	v_mul_f32_e32 v125, v125, v165
	v_cvt_pk_fp8_f32 v138, v112, v113
	v_cvt_pk_fp8_f32 v139, v116, v117
	v_cvt_f32_ubyte2_e32 v163, v130
	v_cvt_f32_ubyte3_e32 v130, v130
	v_cvt_f32_ubyte2_e32 v166, v131
	v_cvt_f32_ubyte3_e32 v131, v131
	v_max_f32_e32 v155, 0.5, v155
	v_max_f32_e32 v132, 0.5, v132
	v_max_f32_e32 v160, 0.5, v160
	v_max_f32_e32 v133, 0.5, v133
	v_cvt_pk_fp8_f32 v140, v120, v121
	v_cvt_pk_fp8_f32 v141, v124, v125
	v_max_f32_e32 v163, 0.5, v163
	v_max_f32_e32 v130, 0.5, v130
	v_max_f32_e32 v166, 0.5, v166
	v_max_f32_e32 v131, 0.5, v131
	v_mul_f32_e32 v155, 0x3a008081, v155
	v_mul_f32_e32 v132, 0x3a008081, v132
	v_mul_f32_e32 v160, 0x3a008081, v160
	v_mul_f32_e32 v133, 0x3a008081, v133
	v_mul_f32_e32 v163, 0x3a008081, v163
	v_mul_f32_e32 v130, 0x3a008081, v130
	v_mul_f32_e32 v166, 0x3a008081, v166
	v_mul_f32_e32 v131, 0x3a008081, v131
	v_mul_f32_e32 v114, v114, v155
	v_mul_f32_e32 v115, v115, v132
	v_mul_f32_e32 v118, v118, v160
	v_mul_f32_e32 v119, v119, v133
	v_mul_f32_e32 v122, v122, v163
	v_mul_f32_e32 v123, v123, v130
	v_mul_f32_e32 v126, v126, v166
	v_mul_f32_e32 v127, v127, v131
	v_cvt_pk_fp8_f32 v138, v114, v115 op_sel:[0,0,1]
	v_cvt_pk_fp8_f32 v139, v118, v119 op_sel:[0,0,1]
	v_cvt_pk_fp8_f32 v140, v122, v123 op_sel:[0,0,1]
	v_cvt_pk_fp8_f32 v141, v126, v127 op_sel:[0,0,1]
	v_lshl_add_u64 v[112:113], s[42:43], 0, v[156:157]
	global_store_dwordx2 v[144:145], v[138:139], off
	global_store_dwordx2 v[144:145], v[140:141], off offset:128
	v_lshl_add_u64 v[112:113], v[112:113], 0, v[134:135]
	s_waitcnt vmcnt(14)
; __device__ __forceinline__ unsigned pk4_fp8g(float a, float b, float c, float d) { int r = __builtin_amdgcn_cvt_pk_fp8_f32(a, b, 0, false); r = __builtin_amdgcn_cvt_pk_fp8_f32(c, d, r, true); return (unsigned)r; }
; #define G2B(bw, sh) (fmaxf((float)(((bw) >> (sh)) & 0xffu), 0.5f) * (1.f / 2040.f))
;     __device__ __forceinline__ void operator()(const f32x4 (&acc)[2][2][4][2], const Unit& u, int wr, int wc, int fr, int fq) const {
;     ...
;             for (int m = 0; m < 4; ++m) { const size_t r = (size_t)(row0 + ai * HALF + m * 16);
; #pragma unroll
;                 for (int bj = 0; bj < 2; ++bj) {
;                     const u32x2g b = *(const u32x2g*)(Gt + r * GC + DM + col0 + bj * HALF);
;                     f32x4 v0 = acc[ai][bj][m][0], v1 = acc[ai][bj][m][1];
;     ...
;                     v0[0] *= G2B(b.x, 0); v0[1] *= G2B(b.x, 8); v0[2] *= G2B(b.x, 16); v0[3] *= G2B(b.x, 24);
;                     v1[0] *= G2B(b.y, 0); v1[1] *= G2B(b.y, 8); v1[2] *= G2B(b.y, 16); v1[3] *= G2B(b.y, 24);
;     ...
;                     u32x2g w; w.x = pk4_fp8g(v0[0], v0[1], v0[2], v0[3]); w.y = pk4_fp8g(v1[0], v1[1], v1[2], v1[3]);
;                     *(u32x2g*)((unsigned char*)O + r * DM + col0 + bj * HALF) = w; }
	v_mov_b64_e32 v[114:115], v[182:183]
	s_nop 0
	v_mov_b64_e32 v[112:113], v[184:185]
	v_mov_b32_e32 v116, v129
	v_mov_b32_e32 v117, v129
	v_mov_b32_e32 v118, v129
	v_mov_b32_e32 v119, v129
	v_add_u32_e32 v120, 32, v136
	v_lshlrev_b64 v[122:123], 10, v[142:143]
	v_ashrrev_i32_e32 v121, 31, v120
	v_lshl_add_u64 v[122:123], s[28:29], 0, v[122:123]
	v_lshlrev_b64 v[124:125], 11, v[120:121]
	v_lshl_add_u64 v[124:125], s[42:43], 0, v[124:125]
	v_cvt_f32_ubyte0_e32 v126, v114
	v_cvt_f32_ubyte1_e32 v127, v114
	v_cvt_f32_ubyte0_e32 v130, v115
	v_cvt_f32_ubyte1_e32 v131, v115
	v_cvt_f32_ubyte0_e32 v133, v112
	v_cvt_f32_ubyte1_e32 v137, v112
	v_cvt_f32_ubyte0_e32 v139, v113
	v_cvt_f32_ubyte1_e32 v140, v113
	v_max_f32_e32 v126, 0.5, v126
	v_max_f32_e32 v127, 0.5, v127
	v_max_f32_e32 v130, 0.5, v130
	v_max_f32_e32 v131, 0.5, v131
	v_max_f32_e32 v133, 0.5, v133
	v_max_f32_e32 v137, 0.5, v137
	v_max_f32_e32 v139, 0.5, v139
	v_max_f32_e32 v140, 0.5, v140
	v_mul_f32_e32 v126, 0x3a008081, v126
	v_mul_f32_e32 v127, 0x3a008081, v127
	v_mul_f32_e32 v130, 0x3a008081, v130
	v_mul_f32_e32 v131, 0x3a008081, v131
	v_mul_f32_e32 v133, 0x3a008081, v133
	v_mul_f32_e32 v137, 0x3a008081, v137
	v_mul_f32_e32 v139, 0x3a008081, v139
	v_mul_f32_e32 v140, 0x3a008081, v140
	v_mul_f32_e32 v96, v96, v126
	v_mul_f32_e32 v97, v97, v127
	v_mul_f32_e32 v100, v100, v130
	v_mul_f32_e32 v101, v101, v131
	v_cvt_f32_ubyte2_e32 v128, v114
	v_cvt_f32_ubyte3_e32 v114, v114
	v_cvt_f32_ubyte2_e32 v132, v115
	v_cvt_f32_ubyte3_e32 v115, v115
	v_mul_f32_e32 v104, v104, v133
	v_mul_f32_e32 v105, v105, v137
	v_mul_f32_e32 v108, v108, v139
	v_mul_f32_e32 v109, v109, v140
	v_cvt_pk_fp8_f32 v116, v96, v97
	v_cvt_pk_fp8_f32 v117, v100, v101
	v_cvt_f32_ubyte2_e32 v138, v112
	v_cvt_f32_ubyte3_e32 v112, v112
	v_cvt_f32_ubyte2_e32 v141, v113
	v_cvt_f32_ubyte3_e32 v113, v113
	v_max_f32_e32 v128, 0.5, v128
	v_max_f32_e32 v114, 0.5, v114
	v_max_f32_e32 v132, 0.5, v132
	v_max_f32_e32 v115, 0.5, v115
	v_cvt_pk_fp8_f32 v118, v104, v105
	v_cvt_pk_fp8_f32 v119, v108, v109
	v_max_f32_e32 v138, 0.5, v138
	v_max_f32_e32 v112, 0.5, v112
	v_max_f32_e32 v141, 0.5, v141
	v_max_f32_e32 v113, 0.5, v113
	v_mul_f32_e32 v128, 0x3a008081, v128
	v_mul_f32_e32 v114, 0x3a008081, v114
	v_mul_f32_e32 v132, 0x3a008081, v132
	v_mul_f32_e32 v115, 0x3a008081, v115
	v_mul_f32_e32 v138, 0x3a008081, v138
	v_mul_f32_e32 v112, 0x3a008081, v112
	v_mul_f32_e32 v141, 0x3a008081, v141
	v_mul_f32_e32 v113, 0x3a008081, v113
	v_mul_f32_e32 v98, v98, v128
	v_mul_f32_e32 v99, v99, v114
	v_mul_f32_e32 v102, v102, v132
	v_mul_f32_e32 v103, v103, v115
	v_mul_f32_e32 v106, v106, v138
	v_mul_f32_e32 v107, v107, v112
	v_mul_f32_e32 v110, v110, v141
	v_mul_f32_e32 v111, v111, v113
	v_cvt_pk_fp8_f32 v116, v98, v99 op_sel:[0,0,1]
	v_cvt_pk_fp8_f32 v117, v102, v103 op_sel:[0,0,1]
	v_cvt_pk_fp8_f32 v118, v106, v107 op_sel:[0,0,1]
	v_cvt_pk_fp8_f32 v119, v110, v111 op_sel:[0,0,1]
	v_lshl_add_u64 v[96:97], v[122:123], 0, v[134:135]
	global_store_dwordx2 v[96:97], v[116:117], off
	global_store_dwordx2 v[96:97], v[118:119], off offset:128
	v_lshl_add_u64 v[98:99], v[124:125], 0, v[134:135]
	s_waitcnt vmcnt(14)
	v_mov_b64_e32 v[96:97], v[186:187]
	s_nop 0
	v_mov_b64_e32 v[98:99], v[188:189]
	v_lshlrev_b64 v[106:107], 10, v[120:121]
	v_mov_b32_e32 v100, v129
	v_mov_b32_e32 v101, v129
	v_mov_b32_e32 v102, v129
	v_mov_b32_e32 v103, v129
	v_add_u32_e32 v104, 48, v136
	v_ashrrev_i32_e32 v105, 31, v104
	v_lshl_add_u64 v[106:107], s[28:29], 0, v[106:107]
	v_lshlrev_b64 v[108:109], 11, v[104:105]
	v_lshl_add_u64 v[108:109], s[42:43], 0, v[108:109]
	v_cvt_f32_ubyte0_e32 v110, v96
	v_cvt_f32_ubyte1_e32 v111, v96
	v_cvt_f32_ubyte0_e32 v113, v97
	v_cvt_f32_ubyte1_e32 v114, v97
	v_cvt_f32_ubyte0_e32 v116, v98
	v_cvt_f32_ubyte1_e32 v117, v98
	v_cvt_f32_ubyte0_e32 v119, v99
	v_cvt_f32_ubyte1_e32 v120, v99
	v_max_f32_e32 v110, 0.5, v110
	v_max_f32_e32 v111, 0.5, v111
	v_max_f32_e32 v113, 0.5, v113
	v_max_f32_e32 v114, 0.5, v114
	v_max_f32_e32 v116, 0.5, v116
	v_max_f32_e32 v117, 0.5, v117
	v_max_f32_e32 v119, 0.5, v119
	v_max_f32_e32 v120, 0.5, v120
	v_mul_f32_e32 v110, 0x3a008081, v110
	v_mul_f32_e32 v111, 0x3a008081, v111
	v_mul_f32_e32 v113, 0x3a008081, v113
	v_mul_f32_e32 v114, 0x3a008081, v114
	v_mul_f32_e32 v116, 0x3a008081, v116
	v_mul_f32_e32 v117, 0x3a008081, v117
	v_mul_f32_e32 v119, 0x3a008081, v119
	v_mul_f32_e32 v120, 0x3a008081, v120
	v_mul_f32_e32 v80, v80, v110
	v_mul_f32_e32 v81, v81, v111
	v_mul_f32_e32 v84, v84, v113
	v_mul_f32_e32 v85, v85, v114
	v_cvt_f32_ubyte2_e32 v112, v96
	v_cvt_f32_ubyte3_e32 v96, v96
	v_cvt_f32_ubyte2_e32 v115, v97
	v_cvt_f32_ubyte3_e32 v97, v97
	v_mul_f32_e32 v88, v88, v116
	v_mul_f32_e32 v89, v89, v117
	v_mul_f32_e32 v92, v92, v119
	v_mul_f32_e32 v93, v93, v120
	v_cvt_pk_fp8_f32 v100, v80, v81
	v_cvt_pk_fp8_f32 v101, v84, v85
	v_cvt_f32_ubyte2_e32 v118, v98
	v_cvt_f32_ubyte3_e32 v98, v98
	v_cvt_f32_ubyte2_e32 v121, v99
	v_cvt_f32_ubyte3_e32 v99, v99
	v_max_f32_e32 v112, 0.5, v112
	v_max_f32_e32 v96, 0.5, v96
	v_max_f32_e32 v115, 0.5, v115
	v_max_f32_e32 v97, 0.5, v97
	v_cvt_pk_fp8_f32 v102, v88, v89
	v_cvt_pk_fp8_f32 v103, v92, v93
	v_max_f32_e32 v118, 0.5, v118
	v_max_f32_e32 v98, 0.5, v98
	v_max_f32_e32 v121, 0.5, v121
	v_max_f32_e32 v99, 0.5, v99
	v_mul_f32_e32 v112, 0x3a008081, v112
	v_mul_f32_e32 v96, 0x3a008081, v96
	v_mul_f32_e32 v115, 0x3a008081, v115
	v_mul_f32_e32 v97, 0x3a008081, v97
	v_mul_f32_e32 v118, 0x3a008081, v118
	v_mul_f32_e32 v98, 0x3a008081, v98
	v_mul_f32_e32 v121, 0x3a008081, v121
	v_mul_f32_e32 v99, 0x3a008081, v99
	v_mul_f32_e32 v82, v82, v112
	v_mul_f32_e32 v83, v83, v96
	v_mul_f32_e32 v86, v86, v115
	v_mul_f32_e32 v87, v87, v97
	v_mul_f32_e32 v90, v90, v118
	v_mul_f32_e32 v91, v91, v98
	v_mul_f32_e32 v94, v94, v121
	v_mul_f32_e32 v95, v95, v99
	v_cvt_pk_fp8_f32 v100, v82, v83 op_sel:[0,0,1]
	v_cvt_pk_fp8_f32 v101, v86, v87 op_sel:[0,0,1]
	v_cvt_pk_fp8_f32 v102, v90, v91 op_sel:[0,0,1]
	v_cvt_pk_fp8_f32 v103, v94, v95 op_sel:[0,0,1]
	v_lshl_add_u64 v[80:81], v[106:107], 0, v[134:135]
	global_store_dwordx2 v[80:81], v[100:101], off
	global_store_dwordx2 v[80:81], v[102:103], off offset:128
	v_lshl_add_u64 v[82:83], v[108:109], 0, v[134:135]
	s_waitcnt vmcnt(14)
; __device__ __forceinline__ unsigned pk4_fp8g(float a, float b, float c, float d) { int r = __builtin_amdgcn_cvt_pk_fp8_f32(a, b, 0, false); r = __builtin_amdgcn_cvt_pk_fp8_f32(c, d, r, true); return (unsigned)r; }
; #define G2B(bw, sh) (fmaxf((float)(((bw) >> (sh)) & 0xffu), 0.5f) * (1.f / 2040.f))
;     __device__ __forceinline__ void operator()(const f32x4 (&acc)[2][2][4][2], const Unit& u, int wr, int wc, int fr, int fq) const {
;     ...
;             for (int m = 0; m < 4; ++m) { const size_t r = (size_t)(row0 + ai * HALF + m * 16);
; #pragma unroll
;                 for (int bj = 0; bj < 2; ++bj) {
;                     const u32x2g b = *(const u32x2g*)(Gt + r * GC + DM + col0 + bj * HALF);
;                     f32x4 v0 = acc[ai][bj][m][0], v1 = acc[ai][bj][m][1];
;     ...
;                     v0[0] *= G2B(b.x, 0); v0[1] *= G2B(b.x, 8); v0[2] *= G2B(b.x, 16); v0[3] *= G2B(b.x, 24);
;                     v1[0] *= G2B(b.y, 0); v1[1] *= G2B(b.y, 8); v1[2] *= G2B(b.y, 16); v1[3] *= G2B(b.y, 24);
;     ...
;                     u32x2g w; w.x = pk4_fp8g(v0[0], v0[1], v0[2], v0[3]); w.y = pk4_fp8g(v1[0], v1[1], v1[2], v1[3]);
;                     *(u32x2g*)((unsigned char*)O + r * DM + col0 + bj * HALF) = w; }
	v_mov_b64_e32 v[80:81], v[190:191]
	s_nop 0
	v_mov_b64_e32 v[82:83], v[192:193]
	v_lshlrev_b64 v[90:91], 10, v[104:105]
	v_mov_b32_e32 v84, v129
	v_mov_b32_e32 v85, v129
	v_mov_b32_e32 v86, v129
	v_mov_b32_e32 v87, v129
	v_add_u32_e32 v88, 0x80, v136
	v_ashrrev_i32_e32 v89, 31, v88
	v_lshl_add_u64 v[90:91], s[28:29], 0, v[90:91]
	v_lshlrev_b64 v[92:93], 11, v[88:89]
	v_lshl_add_u64 v[92:93], s[42:43], 0, v[92:93]
	v_cvt_f32_ubyte0_e32 v94, v80
	v_cvt_f32_ubyte1_e32 v95, v80
	v_cvt_f32_ubyte0_e32 v97, v81
	v_cvt_f32_ubyte1_e32 v98, v81
	v_cvt_f32_ubyte0_e32 v100, v82
	v_cvt_f32_ubyte1_e32 v101, v82
	v_cvt_f32_ubyte0_e32 v103, v83
	v_cvt_f32_ubyte1_e32 v104, v83
	v_max_f32_e32 v94, 0.5, v94
	v_max_f32_e32 v95, 0.5, v95
	v_max_f32_e32 v97, 0.5, v97
	v_max_f32_e32 v98, 0.5, v98
	v_max_f32_e32 v100, 0.5, v100
	v_max_f32_e32 v101, 0.5, v101
	v_max_f32_e32 v103, 0.5, v103
	v_max_f32_e32 v104, 0.5, v104
	v_mul_f32_e32 v94, 0x3a008081, v94
	v_mul_f32_e32 v95, 0x3a008081, v95
	v_mul_f32_e32 v97, 0x3a008081, v97
	v_mul_f32_e32 v98, 0x3a008081, v98
	v_mul_f32_e32 v100, 0x3a008081, v100
	v_mul_f32_e32 v101, 0x3a008081, v101
	v_mul_f32_e32 v103, 0x3a008081, v103
	v_mul_f32_e32 v104, 0x3a008081, v104
	v_mul_f32_e32 v64, v64, v94
	v_mul_f32_e32 v65, v65, v95
	v_mul_f32_e32 v68, v68, v97
	v_mul_f32_e32 v69, v69, v98
	v_cvt_f32_ubyte2_e32 v96, v80
	v_cvt_f32_ubyte3_e32 v80, v80
	v_cvt_f32_ubyte2_e32 v99, v81
	v_cvt_f32_ubyte3_e32 v81, v81
	v_mul_f32_e32 v72, v72, v100
	v_mul_f32_e32 v73, v73, v101
	v_mul_f32_e32 v76, v76, v103
	v_mul_f32_e32 v77, v77, v104
	v_cvt_pk_fp8_f32 v84, v64, v65
	v_cvt_pk_fp8_f32 v85, v68, v69
	v_cvt_f32_ubyte2_e32 v102, v82
	v_cvt_f32_ubyte3_e32 v82, v82
	v_cvt_f32_ubyte2_e32 v105, v83
	v_cvt_f32_ubyte3_e32 v83, v83
	v_max_f32_e32 v96, 0.5, v96
	v_max_f32_e32 v80, 0.5, v80
	v_max_f32_e32 v99, 0.5, v99
	v_max_f32_e32 v81, 0.5, v81
	v_cvt_pk_fp8_f32 v86, v72, v73
	v_cvt_pk_fp8_f32 v87, v76, v77
	v_max_f32_e32 v102, 0.5, v102
	v_max_f32_e32 v82, 0.5, v82
	v_max_f32_e32 v105, 0.5, v105
	v_max_f32_e32 v83, 0.5, v83
	v_mul_f32_e32 v96, 0x3a008081, v96
	v_mul_f32_e32 v80, 0x3a008081, v80
	v_mul_f32_e32 v99, 0x3a008081, v99
	v_mul_f32_e32 v81, 0x3a008081, v81
	v_mul_f32_e32 v102, 0x3a008081, v102
	v_mul_f32_e32 v82, 0x3a008081, v82
	v_mul_f32_e32 v105, 0x3a008081, v105
	v_mul_f32_e32 v83, 0x3a008081, v83
	v_mul_f32_e32 v66, v66, v96
	v_mul_f32_e32 v67, v67, v80
	v_mul_f32_e32 v70, v70, v99
	v_mul_f32_e32 v71, v71, v81
	v_mul_f32_e32 v74, v74, v102
	v_mul_f32_e32 v75, v75, v82
	v_mul_f32_e32 v78, v78, v105
	v_mul_f32_e32 v79, v79, v83
	v_cvt_pk_fp8_f32 v84, v66, v67 op_sel:[0,0,1]
	v_cvt_pk_fp8_f32 v85, v70, v71 op_sel:[0,0,1]
	v_cvt_pk_fp8_f32 v86, v74, v75 op_sel:[0,0,1]
	v_cvt_pk_fp8_f32 v87, v78, v79 op_sel:[0,0,1]
	v_lshl_add_u64 v[64:65], v[90:91], 0, v[134:135]
	global_store_dwordx2 v[64:65], v[84:85], off
	global_store_dwordx2 v[64:65], v[86:87], off offset:128
	v_lshl_add_u64 v[66:67], v[92:93], 0, v[134:135]
	s_waitcnt vmcnt(14)
	v_mov_b64_e32 v[64:65], v[194:195]
	s_nop 0
	v_mov_b64_e32 v[66:67], v[196:197]
	v_lshlrev_b64 v[74:75], 10, v[88:89]
	v_mov_b32_e32 v68, v129
	v_mov_b32_e32 v69, v129
	v_mov_b32_e32 v70, v129
	v_mov_b32_e32 v71, v129
	v_add_u32_e32 v72, 0x90, v136
	v_ashrrev_i32_e32 v73, 31, v72
	v_lshl_add_u64 v[74:75], s[28:29], 0, v[74:75]
	v_lshlrev_b64 v[76:77], 11, v[72:73]
	v_lshl_add_u64 v[76:77], s[42:43], 0, v[76:77]
	v_cvt_f32_ubyte0_e32 v78, v64
	v_cvt_f32_ubyte1_e32 v79, v64
	v_cvt_f32_ubyte0_e32 v81, v65
	v_cvt_f32_ubyte1_e32 v82, v65
	v_cvt_f32_ubyte0_e32 v84, v66
	v_cvt_f32_ubyte1_e32 v85, v66
	v_cvt_f32_ubyte0_e32 v87, v67
	v_cvt_f32_ubyte1_e32 v88, v67
	v_max_f32_e32 v78, 0.5, v78
	v_max_f32_e32 v79, 0.5, v79
	v_max_f32_e32 v81, 0.5, v81
	v_max_f32_e32 v82, 0.5, v82
	v_max_f32_e32 v84, 0.5, v84
	v_max_f32_e32 v85, 0.5, v85
	v_max_f32_e32 v87, 0.5, v87
	v_max_f32_e32 v88, 0.5, v88
	v_mul_f32_e32 v78, 0x3a008081, v78
	v_mul_f32_e32 v79, 0x3a008081, v79
	v_mul_f32_e32 v81, 0x3a008081, v81
	v_mul_f32_e32 v82, 0x3a008081, v82
	v_mul_f32_e32 v84, 0x3a008081, v84
	v_mul_f32_e32 v85, 0x3a008081, v85
	v_mul_f32_e32 v87, 0x3a008081, v87
	v_mul_f32_e32 v88, 0x3a008081, v88
	v_mul_f32_e32 v48, v48, v78
	v_mul_f32_e32 v49, v49, v79
	v_mul_f32_e32 v52, v52, v81
	v_mul_f32_e32 v53, v53, v82
	v_cvt_f32_ubyte2_e32 v80, v64
	v_cvt_f32_ubyte3_e32 v64, v64
	v_cvt_f32_ubyte2_e32 v83, v65
	v_cvt_f32_ubyte3_e32 v65, v65
	v_mul_f32_e32 v56, v56, v84
	v_mul_f32_e32 v57, v57, v85
	v_mul_f32_e32 v60, v60, v87
	v_mul_f32_e32 v61, v61, v88
	v_cvt_pk_fp8_f32 v68, v48, v49
	v_cvt_pk_fp8_f32 v69, v52, v53
	v_cvt_f32_ubyte2_e32 v86, v66
	v_cvt_f32_ubyte3_e32 v66, v66
	v_cvt_f32_ubyte2_e32 v89, v67
	v_cvt_f32_ubyte3_e32 v67, v67
	v_max_f32_e32 v80, 0.5, v80
	v_max_f32_e32 v64, 0.5, v64
	v_max_f32_e32 v83, 0.5, v83
	v_max_f32_e32 v65, 0.5, v65
	v_cvt_pk_fp8_f32 v70, v56, v57
	v_cvt_pk_fp8_f32 v71, v60, v61
	v_max_f32_e32 v86, 0.5, v86
	v_max_f32_e32 v66, 0.5, v66
	v_max_f32_e32 v89, 0.5, v89
	v_max_f32_e32 v67, 0.5, v67
	v_mul_f32_e32 v80, 0x3a008081, v80
	v_mul_f32_e32 v64, 0x3a008081, v64
	v_mul_f32_e32 v83, 0x3a008081, v83
	v_mul_f32_e32 v65, 0x3a008081, v65
	v_mul_f32_e32 v86, 0x3a008081, v86
	v_mul_f32_e32 v66, 0x3a008081, v66
	v_mul_f32_e32 v89, 0x3a008081, v89
	v_mul_f32_e32 v67, 0x3a008081, v67
	v_mul_f32_e32 v50, v50, v80
	v_mul_f32_e32 v51, v51, v64
	v_mul_f32_e32 v54, v54, v83
	v_mul_f32_e32 v55, v55, v65
	v_mul_f32_e32 v58, v58, v86
	v_mul_f32_e32 v59, v59, v66
	v_mul_f32_e32 v62, v62, v89
	v_mul_f32_e32 v63, v63, v67
	v_cvt_pk_fp8_f32 v68, v50, v51 op_sel:[0,0,1]
	v_cvt_pk_fp8_f32 v69, v54, v55 op_sel:[0,0,1]
	v_cvt_pk_fp8_f32 v70, v58, v59 op_sel:[0,0,1]
	v_cvt_pk_fp8_f32 v71, v62, v63 op_sel:[0,0,1]
	v_lshl_add_u64 v[48:49], v[74:75], 0, v[134:135]
	global_store_dwordx2 v[48:49], v[68:69], off
	global_store_dwordx2 v[48:49], v[70:71], off offset:128
	v_lshl_add_u64 v[50:51], v[76:77], 0, v[134:135]
	s_waitcnt vmcnt(14)
; __device__ __forceinline__ unsigned pk4_fp8g(float a, float b, float c, float d) { int r = __builtin_amdgcn_cvt_pk_fp8_f32(a, b, 0, false); r = __builtin_amdgcn_cvt_pk_fp8_f32(c, d, r, true); return (unsigned)r; }
; #define G2B(bw, sh) (fmaxf((float)(((bw) >> (sh)) & 0xffu), 0.5f) * (1.f / 2040.f))
;     __device__ __forceinline__ void operator()(const f32x4 (&acc)[2][2][4][2], const Unit& u, int wr, int wc, int fr, int fq) const {
;     ...
;             for (int m = 0; m < 4; ++m) { const size_t r = (size_t)(row0 + ai * HALF + m * 16);
; #pragma unroll
;                 for (int bj = 0; bj < 2; ++bj) {
;                     const u32x2g b = *(const u32x2g*)(Gt + r * GC + DM + col0 + bj * HALF);
;                     f32x4 v0 = acc[ai][bj][m][0], v1 = acc[ai][bj][m][1];
;     ...
;                     v0[0] *= G2B(b.x, 0); v0[1] *= G2B(b.x, 8); v0[2] *= G2B(b.x, 16); v0[3] *= G2B(b.x, 24);
;                     v1[0] *= G2B(b.y, 0); v1[1] *= G2B(b.y, 8); v1[2] *= G2B(b.y, 16); v1[3] *= G2B(b.y, 24);
;     ...
;                     u32x2g w; w.x = pk4_fp8g(v0[0], v0[1], v0[2], v0[3]); w.y = pk4_fp8g(v1[0], v1[1], v1[2], v1[3]);
;                     *(u32x2g*)((unsigned char*)O + r * DM + col0 + bj * HALF) = w; }
	v_mov_b64_e32 v[48:49], v[198:199]
	s_nop 0
	v_mov_b64_e32 v[50:51], v[200:201]
	v_lshlrev_b64 v[58:59], 10, v[72:73]
	v_mov_b32_e32 v52, v129
	v_mov_b32_e32 v53, v129
	v_mov_b32_e32 v54, v129
	v_mov_b32_e32 v55, v129
	v_add_u32_e32 v56, 0xa0, v136
	v_ashrrev_i32_e32 v57, 31, v56
	v_lshl_add_u64 v[58:59], s[28:29], 0, v[58:59]
	v_lshlrev_b64 v[60:61], 11, v[56:57]
	v_lshl_add_u64 v[60:61], s[42:43], 0, v[60:61]
	v_cvt_f32_ubyte0_e32 v62, v48
	v_cvt_f32_ubyte1_e32 v63, v48
	v_cvt_f32_ubyte0_e32 v65, v49
	v_cvt_f32_ubyte1_e32 v66, v49
	v_cvt_f32_ubyte0_e32 v68, v50
	v_cvt_f32_ubyte1_e32 v69, v50
	v_cvt_f32_ubyte0_e32 v71, v51
	v_cvt_f32_ubyte1_e32 v72, v51
	v_max_f32_e32 v62, 0.5, v62
	v_max_f32_e32 v63, 0.5, v63
	v_max_f32_e32 v65, 0.5, v65
	v_max_f32_e32 v66, 0.5, v66
	v_max_f32_e32 v68, 0.5, v68
	v_max_f32_e32 v69, 0.5, v69
	v_max_f32_e32 v71, 0.5, v71
	v_max_f32_e32 v72, 0.5, v72
	v_mul_f32_e32 v62, 0x3a008081, v62
	v_mul_f32_e32 v63, 0x3a008081, v63
	v_mul_f32_e32 v65, 0x3a008081, v65
	v_mul_f32_e32 v66, 0x3a008081, v66
	v_mul_f32_e32 v68, 0x3a008081, v68
	v_mul_f32_e32 v69, 0x3a008081, v69
	v_mul_f32_e32 v71, 0x3a008081, v71
	v_mul_f32_e32 v72, 0x3a008081, v72
	v_mul_f32_e32 v32, v32, v62
	v_mul_f32_e32 v33, v33, v63
	v_mul_f32_e32 v36, v36, v65
	v_mul_f32_e32 v37, v37, v66
	v_cvt_f32_ubyte2_e32 v64, v48
	v_cvt_f32_ubyte3_e32 v48, v48
	v_cvt_f32_ubyte2_e32 v67, v49
	v_cvt_f32_ubyte3_e32 v49, v49
	v_mul_f32_e32 v40, v40, v68
	v_mul_f32_e32 v41, v41, v69
	v_mul_f32_e32 v44, v44, v71
	v_mul_f32_e32 v45, v45, v72
	v_cvt_pk_fp8_f32 v52, v32, v33
	v_cvt_pk_fp8_f32 v53, v36, v37
	v_cvt_f32_ubyte2_e32 v70, v50
	v_cvt_f32_ubyte3_e32 v50, v50
	v_cvt_f32_ubyte2_e32 v73, v51
	v_cvt_f32_ubyte3_e32 v51, v51
	v_max_f32_e32 v64, 0.5, v64
	v_max_f32_e32 v48, 0.5, v48
	v_max_f32_e32 v67, 0.5, v67
	v_max_f32_e32 v49, 0.5, v49
	v_cvt_pk_fp8_f32 v54, v40, v41
	v_cvt_pk_fp8_f32 v55, v44, v45
	v_max_f32_e32 v70, 0.5, v70
	v_max_f32_e32 v50, 0.5, v50
	v_max_f32_e32 v73, 0.5, v73
	v_max_f32_e32 v51, 0.5, v51
	v_mul_f32_e32 v64, 0x3a008081, v64
	v_mul_f32_e32 v48, 0x3a008081, v48
	v_mul_f32_e32 v67, 0x3a008081, v67
	v_mul_f32_e32 v49, 0x3a008081, v49
	v_mul_f32_e32 v70, 0x3a008081, v70
	v_mul_f32_e32 v50, 0x3a008081, v50
	v_mul_f32_e32 v73, 0x3a008081, v73
	v_mul_f32_e32 v51, 0x3a008081, v51
	v_mul_f32_e32 v34, v34, v64
	v_mul_f32_e32 v35, v35, v48
	v_mul_f32_e32 v38, v38, v67
	v_mul_f32_e32 v39, v39, v49
	v_mul_f32_e32 v42, v42, v70
	v_mul_f32_e32 v43, v43, v50
	v_mul_f32_e32 v46, v46, v73
	v_mul_f32_e32 v47, v47, v51
	v_cvt_pk_fp8_f32 v52, v34, v35 op_sel:[0,0,1]
	v_cvt_pk_fp8_f32 v53, v38, v39 op_sel:[0,0,1]
	v_cvt_pk_fp8_f32 v54, v42, v43 op_sel:[0,0,1]
	v_cvt_pk_fp8_f32 v55, v46, v47 op_sel:[0,0,1]
	v_lshl_add_u64 v[32:33], v[58:59], 0, v[134:135]
	global_store_dwordx2 v[32:33], v[52:53], off
	global_store_dwordx2 v[32:33], v[54:55], off offset:128
	v_lshl_add_u64 v[34:35], v[60:61], 0, v[134:135]
	s_waitcnt vmcnt(14)
	v_mov_b64_e32 v[32:33], v[202:203]
	s_nop 0
	v_mov_b64_e32 v[34:35], v[204:205]
	v_lshlrev_b64 v[42:43], 10, v[56:57]
	v_mov_b32_e32 v36, v129
	v_mov_b32_e32 v37, v129
	v_mov_b32_e32 v38, v129
	v_mov_b32_e32 v39, v129
	v_add_u32_e32 v40, 0xb0, v136
	v_ashrrev_i32_e32 v41, 31, v40
	v_lshl_add_u64 v[42:43], s[28:29], 0, v[42:43]
	v_lshlrev_b64 v[44:45], 11, v[40:41]
	v_lshl_add_u64 v[44:45], s[42:43], 0, v[44:45]
	v_cvt_f32_ubyte0_e32 v46, v32
	v_cvt_f32_ubyte1_e32 v47, v32
	v_cvt_f32_ubyte0_e32 v49, v33
	v_cvt_f32_ubyte1_e32 v50, v33
	v_cvt_f32_ubyte0_e32 v52, v34
	v_cvt_f32_ubyte1_e32 v53, v34
	v_cvt_f32_ubyte0_e32 v55, v35
	v_cvt_f32_ubyte1_e32 v56, v35
	v_max_f32_e32 v46, 0.5, v46
	v_max_f32_e32 v47, 0.5, v47
	v_max_f32_e32 v49, 0.5, v49
	v_max_f32_e32 v50, 0.5, v50
	v_max_f32_e32 v52, 0.5, v52
	v_max_f32_e32 v53, 0.5, v53
	v_max_f32_e32 v55, 0.5, v55
	v_max_f32_e32 v56, 0.5, v56
	v_mul_f32_e32 v46, 0x3a008081, v46
	v_mul_f32_e32 v47, 0x3a008081, v47
	v_mul_f32_e32 v49, 0x3a008081, v49
	v_mul_f32_e32 v50, 0x3a008081, v50
	v_mul_f32_e32 v52, 0x3a008081, v52
	v_mul_f32_e32 v53, 0x3a008081, v53
	v_mul_f32_e32 v55, 0x3a008081, v55
	v_mul_f32_e32 v56, 0x3a008081, v56
	v_mul_f32_e32 v16, v16, v46
	v_mul_f32_e32 v17, v17, v47
	v_mul_f32_e32 v20, v20, v49
	v_mul_f32_e32 v21, v21, v50
	v_cvt_f32_ubyte2_e32 v48, v32
	v_cvt_f32_ubyte3_e32 v32, v32
	v_cvt_f32_ubyte2_e32 v51, v33
	v_cvt_f32_ubyte3_e32 v33, v33
	v_mul_f32_e32 v24, v24, v52
	v_mul_f32_e32 v25, v25, v53
	v_mul_f32_e32 v28, v28, v55
	v_mul_f32_e32 v29, v29, v56
	v_cvt_pk_fp8_f32 v36, v16, v17
	v_cvt_pk_fp8_f32 v37, v20, v21
	v_cvt_f32_ubyte2_e32 v54, v34
	v_cvt_f32_ubyte3_e32 v34, v34
	v_cvt_f32_ubyte2_e32 v57, v35
	v_cvt_f32_ubyte3_e32 v35, v35
	v_max_f32_e32 v48, 0.5, v48
	v_max_f32_e32 v32, 0.5, v32
	v_max_f32_e32 v51, 0.5, v51
	v_max_f32_e32 v33, 0.5, v33
	v_cvt_pk_fp8_f32 v38, v24, v25
	v_cvt_pk_fp8_f32 v39, v28, v29
	v_max_f32_e32 v54, 0.5, v54
	v_max_f32_e32 v34, 0.5, v34
	v_max_f32_e32 v57, 0.5, v57
	v_max_f32_e32 v35, 0.5, v35
	v_mul_f32_e32 v48, 0x3a008081, v48
	v_mul_f32_e32 v32, 0x3a008081, v32
	v_mul_f32_e32 v51, 0x3a008081, v51
	v_mul_f32_e32 v33, 0x3a008081, v33
	v_mul_f32_e32 v54, 0x3a008081, v54
	v_mul_f32_e32 v34, 0x3a008081, v34
	v_mul_f32_e32 v57, 0x3a008081, v57
	v_mul_f32_e32 v35, 0x3a008081, v35
	v_mul_f32_e32 v18, v18, v48
	v_mul_f32_e32 v19, v19, v32
	v_mul_f32_e32 v22, v22, v51
	v_mul_f32_e32 v23, v23, v33
	v_mul_f32_e32 v26, v26, v54
	v_mul_f32_e32 v27, v27, v34
	v_mul_f32_e32 v30, v30, v57
	v_mul_f32_e32 v31, v31, v35
	v_cvt_pk_fp8_f32 v36, v18, v19 op_sel:[0,0,1]
	v_cvt_pk_fp8_f32 v37, v22, v23 op_sel:[0,0,1]
	v_cvt_pk_fp8_f32 v38, v26, v27 op_sel:[0,0,1]
	v_cvt_pk_fp8_f32 v39, v30, v31 op_sel:[0,0,1]
	v_lshl_add_u64 v[16:17], v[42:43], 0, v[134:135]
	global_store_dwordx2 v[16:17], v[36:37], off
	global_store_dwordx2 v[16:17], v[38:39], off offset:128
	v_lshl_add_u64 v[18:19], v[44:45], 0, v[134:135]
	s_waitcnt vmcnt(14)
; #define PG8_BAR __builtin_amdgcn_s_barrier()
; __device__ __forceinline__ unsigned pk4_fp8g(float a, float b, float c, float d) { int r = __builtin_amdgcn_cvt_pk_fp8_f32(a, b, 0, false); r = __builtin_amdgcn_cvt_pk_fp8_f32(c, d, r, true); return (unsigned)r; }
; #define G2B(bw, sh) (fmaxf((float)(((bw) >> (sh)) & 0xffu), 0.5f) * (1.f / 2040.f))
; template <class Epi, class Sched, bool ALIGN_EPI = false, bool SP2 = false, bool FP8 = false>
; __device__ __forceinline__ void gemm_phase(PG8_LAS unsigned char* lds, const Gemm g, const Sched& S, const Epi& E) {
;     ...
;         for (int a = 0; a < 2; ++a)
; #pragma unroll
;             for (int b = 0; b < 2; ++b)
; #pragma unroll
;                 for (int m = 0; m < 4; ++m)
; #pragma unroll
;                     for (int n = 0; n < 2; ++n) { acc[a][b][m][n] = (f32x4){0.f, 0.f, 0.f, 0.f}; if constexpr (FP8) asm volatile("" : "+v"(acc[a][b][m][n])); }
;         cur = nxt; cA = nA; cB = nB; ++ui;
;         if constexpr (ALIGN_EPI) { if (wr == 1) PG8_BAR; }
;     __device__ __forceinline__ void operator()(const f32x4 (&acc)[2][2][4][2], const Unit& u, int wr, int wc, int fr, int fq) const {
;     ...
;                     const u32x2g b = *(const u32x2g*)(Gt + r * GC + DM + col0 + bj * HALF);
;                     f32x4 v0 = acc[ai][bj][m][0], v1 = acc[ai][bj][m][1];
;     ...
;                     v0[0] *= G2B(b.x, 0); v0[1] *= G2B(b.x, 8); v0[2] *= G2B(b.x, 16); v0[3] *= G2B(b.x, 24);
;                     v1[0] *= G2B(b.y, 0); v1[1] *= G2B(b.y, 8); v1[2] *= G2B(b.y, 16); v1[3] *= G2B(b.y, 24);
;     ...
;                     u32x2g w; w.x = pk4_fp8g(v0[0], v0[1], v0[2], v0[3]); w.y = pk4_fp8g(v1[0], v1[1], v1[2], v1[3]);
;                     *(u32x2g*)((unsigned char*)O + r * DM + col0 + bj * HALF) = w; }
	v_mov_b64_e32 v[16:17], v[206:207]
	s_nop 0
	v_mov_b64_e32 v[18:19], v[208:209]
	v_mov_b32_e32 v20, v129
	v_mov_b32_e32 v21, v129
	v_mov_b32_e32 v22, v129
	v_mov_b32_e32 v23, v129
	v_lshlrev_b64 v[24:25], 10, v[40:41]
	v_cvt_f32_ubyte0_e32 v26, v16
	v_cvt_f32_ubyte1_e32 v27, v16
	v_cvt_f32_ubyte0_e32 v29, v17
	v_cvt_f32_ubyte1_e32 v30, v17
	v_cvt_f32_ubyte0_e32 v32, v18
	v_cvt_f32_ubyte1_e32 v33, v18
	v_cvt_f32_ubyte0_e32 v35, v19
	v_cvt_f32_ubyte1_e32 v36, v19
	v_max_f32_e32 v26, 0.5, v26
	v_max_f32_e32 v27, 0.5, v27
	v_max_f32_e32 v29, 0.5, v29
	v_max_f32_e32 v30, 0.5, v30
	v_max_f32_e32 v32, 0.5, v32
	v_max_f32_e32 v33, 0.5, v33
	v_max_f32_e32 v35, 0.5, v35
	v_max_f32_e32 v36, 0.5, v36
	v_mul_f32_e32 v26, 0x3a008081, v26
	v_mul_f32_e32 v27, 0x3a008081, v27
	v_mul_f32_e32 v29, 0x3a008081, v29
	v_mul_f32_e32 v30, 0x3a008081, v30
	v_mul_f32_e32 v32, 0x3a008081, v32
	v_mul_f32_e32 v33, 0x3a008081, v33
	v_mul_f32_e32 v35, 0x3a008081, v35
	v_mul_f32_e32 v36, 0x3a008081, v36
	v_mul_f32_e32 v4, v4, v26
	v_mul_f32_e32 v5, v5, v27
	v_mul_f32_e32 v8, v8, v29
	v_mul_f32_e32 v9, v9, v30
	v_cvt_f32_ubyte2_e32 v28, v16
	v_cvt_f32_ubyte3_e32 v16, v16
	v_cvt_f32_ubyte2_e32 v31, v17
	v_cvt_f32_ubyte3_e32 v17, v17
	v_mul_f32_e32 v12, v12, v32
	v_mul_f32_e32 v13, v13, v33
	v_mul_f32_e32 v0, v0, v35
	v_mul_f32_e32 v1, v1, v36
	v_cvt_pk_fp8_f32 v20, v4, v5
	v_cvt_pk_fp8_f32 v21, v8, v9
	v_cvt_f32_ubyte2_e32 v34, v18
	v_cvt_f32_ubyte3_e32 v18, v18
	v_cvt_f32_ubyte2_e32 v37, v19
	v_cvt_f32_ubyte3_e32 v19, v19
	v_max_f32_e32 v28, 0.5, v28
	v_max_f32_e32 v16, 0.5, v16
	v_max_f32_e32 v31, 0.5, v31
	v_max_f32_e32 v17, 0.5, v17
	v_cvt_pk_fp8_f32 v22, v12, v13
	v_cvt_pk_fp8_f32 v23, v0, v1
	v_max_f32_e32 v34, 0.5, v34
	v_max_f32_e32 v18, 0.5, v18
	v_max_f32_e32 v37, 0.5, v37
	v_max_f32_e32 v19, 0.5, v19
	v_mul_f32_e32 v28, 0x3a008081, v28
	v_mul_f32_e32 v16, 0x3a008081, v16
	v_mul_f32_e32 v31, 0x3a008081, v31
	v_mul_f32_e32 v17, 0x3a008081, v17
	v_mul_f32_e32 v34, 0x3a008081, v34
	v_mul_f32_e32 v18, 0x3a008081, v18
	v_mul_f32_e32 v37, 0x3a008081, v37
	v_mul_f32_e32 v19, 0x3a008081, v19
	v_mul_f32_e32 v6, v6, v28
	v_mul_f32_e32 v7, v7, v16
	v_mul_f32_e32 v10, v10, v31
	v_mul_f32_e32 v11, v11, v17
	v_mul_f32_e32 v14, v14, v34
	v_mul_f32_e32 v15, v15, v18
	v_mul_f32_e32 v2, v2, v37
	v_mul_f32_e32 v3, v3, v19
	v_cvt_pk_fp8_f32 v20, v6, v7 op_sel:[0,0,1]
	v_cvt_pk_fp8_f32 v21, v10, v11 op_sel:[0,0,1]
	v_cvt_pk_fp8_f32 v22, v14, v15 op_sel:[0,0,1]
	v_cvt_pk_fp8_f32 v23, v2, v3 op_sel:[0,0,1]
	v_lshl_add_u64 v[0:1], s[28:29], 0, v[24:25]
	v_lshl_add_u64 v[0:1], v[0:1], 0, v[134:135]
	global_store_dwordx2 v[0:1], v[20:21], off
	global_store_dwordx2 v[0:1], v[22:23], off offset:128
	s_cbranch_vccnz .LBB0_297
	s_mov_b32 s9, s8
	s_mov_b32 s10, s8
	s_mov_b32 s11, s8
	v_mov_b64_e32 v[0:1], s[8:9]
	v_mov_b64_e32 v[114:115], s[10:11]
	v_mov_b64_e32 v[118:119], s[10:11]
	v_mov_b64_e32 v[98:99], s[10:11]
	v_mov_b64_e32 v[102:103], s[10:11]
	v_mov_b64_e32 v[82:83], s[10:11]
	v_mov_b64_e32 v[86:87], s[10:11]
	v_mov_b64_e32 v[66:67], s[10:11]
	v_mov_b64_e32 v[70:71], s[10:11]
	v_mov_b64_e32 v[122:123], s[10:11]
	v_mov_b64_e32 v[126:127], s[10:11]
	v_mov_b64_e32 v[106:107], s[10:11]
	v_mov_b64_e32 v[110:111], s[10:11]
	v_mov_b64_e32 v[90:91], s[10:11]
	v_mov_b64_e32 v[94:95], s[10:11]
	v_mov_b64_e32 v[74:75], s[10:11]
	v_mov_b64_e32 v[78:79], s[10:11]
	v_mov_b64_e32 v[50:51], s[10:11]
	v_mov_b64_e32 v[54:55], s[10:11]
	v_mov_b64_e32 v[34:35], s[10:11]
	v_mov_b64_e32 v[38:39], s[10:11]
	v_mov_b64_e32 v[18:19], s[10:11]
	v_mov_b64_e32 v[22:23], s[10:11]
	v_mov_b64_e32 v[4:5], s[8:9]
	v_mov_b64_e32 v[8:9], s[8:9]
	v_mov_b64_e32 v[58:59], s[10:11]
	v_mov_b64_e32 v[62:63], s[10:11]
	v_mov_b64_e32 v[42:43], s[10:11]
	v_mov_b64_e32 v[46:47], s[10:11]
	v_mov_b64_e32 v[26:27], s[10:11]
	v_mov_b64_e32 v[30:31], s[10:11]
	v_mov_b64_e32 v[14:15], s[10:11]
	v_mov_b64_e32 v[2:3], s[10:11]
	v_mov_b64_e32 v[112:113], s[8:9]
	v_mov_b64_e32 v[116:117], s[8:9]
	v_mov_b64_e32 v[96:97], s[8:9]
	v_mov_b64_e32 v[100:101], s[8:9]
	v_mov_b64_e32 v[80:81], s[8:9]
	v_mov_b64_e32 v[84:85], s[8:9]
	v_mov_b64_e32 v[64:65], s[8:9]
	v_mov_b64_e32 v[68:69], s[8:9]
	v_mov_b64_e32 v[120:121], s[8:9]
	v_mov_b64_e32 v[124:125], s[8:9]
	v_mov_b64_e32 v[104:105], s[8:9]
	v_mov_b64_e32 v[108:109], s[8:9]
	v_mov_b64_e32 v[88:89], s[8:9]
	v_mov_b64_e32 v[92:93], s[8:9]
	v_mov_b64_e32 v[72:73], s[8:9]
	v_mov_b64_e32 v[76:77], s[8:9]
	v_mov_b64_e32 v[48:49], s[8:9]
	v_mov_b64_e32 v[52:53], s[8:9]
	v_mov_b64_e32 v[32:33], s[8:9]
	v_mov_b64_e32 v[36:37], s[8:9]
	v_mov_b64_e32 v[16:17], s[8:9]
	v_mov_b64_e32 v[20:21], s[8:9]
	v_mov_b64_e32 v[6:7], s[10:11]
	v_mov_b64_e32 v[10:11], s[10:11]
	v_mov_b64_e32 v[56:57], s[8:9]
	v_mov_b64_e32 v[60:61], s[8:9]
	v_mov_b64_e32 v[40:41], s[8:9]
	v_mov_b64_e32 v[44:45], s[8:9]
	v_mov_b64_e32 v[24:25], s[8:9]
	v_mov_b64_e32 v[28:29], s[8:9]
	v_mov_b64_e32 v[12:13], s[8:9]
	s_andn2_b64 vcc, exec, s[12:13]
	s_cbranch_vccnz .LBB0_296
	s_mov_b32 s100, 1
	s_branch .LBB0_296
